# DA pipelined ring loop: QK(t+1) MFMAs moved into the pb0 exp/cvt block, row-sum adds rebalanced into PV tail gaps, wave-group-B barrier after PV4
# speedup vs baseline: 1.0028x; 1.0028x over previous
.Lmy_pp_loop2:
	v_add_u32_e32 v248, s25, v246
	v_add_u32_e32 v249, s25, v247
	ds_read_b128 v[144:147], v248 offset:8192
	ds_read_b128 v[136:139], v248 offset:10240
	ds_read_b128 v[132:135], v248 offset:12288
	ds_read_b128 v[116:119], v248 offset:14336
	ds_read_b128 v[128:131], v248 offset:9216
	ds_read_b128 v[140:143], v248 offset:11264
	ds_read_b128 v[124:127], v248 offset:13312
	ds_read_b128 v[120:123], v248 offset:15360
	v_max3_f32 v14, v80, v81, v82
	v_max3_f32 v15, v83, v84, v85
	v_max3_f32 v209, v86, v87, v88
	v_max3_f32 v212, v89, v90, v91
	v_max3_f32 v14, v14, v92, v93
	v_max3_f32 v15, v15, v94, v95
	v_max3_f32 v14, v14, v15, v209
	v_max_f32_e32 v14, v14, v212
	v_mov_b32_e32 v15, v14
	s_mov_b32 m0, s24
	s_sub_i32 s28, 5, s29
	s_cmp_gt_u32 s13, s28
	s_cselect_b32 s28, -1, 0
	v_permlane32_swap_b32_e32 v14, v15
	s_add_i32 s24, s24, 0x4000
	s_and_b32 s24, s24, 0xffff
	v_max_f32_e32 v14, v14, v15
	v_add_f32_e32 v15, 0x41000000, v208
	v_cmp_gt_f32_e32 vcc, v14, v15
	s_cbranch_vccz .Lmy_pp_nors_a
	v_max_f32_e32 v15, v208, v14
	v_sub_f32_e32 v14, v208, v15
	v_exp_f32_e32 v14, v14
	v_mov_b32_e32 v208, v15
	s_nop 0
	v_mul_f32_e32 v0, v0, v14
	v_pk_mul_f32 v[78:79], v[78:79], v[14:15] op_sel_hi:[1,0]
	v_pk_mul_f32 v[76:77], v[76:77], v[14:15] op_sel_hi:[1,0]
	v_pk_mul_f32 v[74:75], v[74:75], v[14:15] op_sel_hi:[1,0]
	v_pk_mul_f32 v[72:73], v[72:73], v[14:15] op_sel_hi:[1,0]
	v_pk_mul_f32 v[70:71], v[70:71], v[14:15] op_sel_hi:[1,0]
	v_pk_mul_f32 v[68:69], v[68:69], v[14:15] op_sel_hi:[1,0]
	v_pk_mul_f32 v[66:67], v[66:67], v[14:15] op_sel_hi:[1,0]
	v_pk_mul_f32 v[64:65], v[64:65], v[14:15] op_sel_hi:[1,0]
	v_pk_mul_f32 v[62:63], v[62:63], v[14:15] op_sel_hi:[1,0]
	v_pk_mul_f32 v[60:61], v[60:61], v[14:15] op_sel_hi:[1,0]
	v_pk_mul_f32 v[58:59], v[58:59], v[14:15] op_sel_hi:[1,0]
	v_pk_mul_f32 v[56:57], v[56:57], v[14:15] op_sel_hi:[1,0]
	v_pk_mul_f32 v[54:55], v[54:55], v[14:15] op_sel_hi:[1,0]
	v_pk_mul_f32 v[52:53], v[52:53], v[14:15] op_sel_hi:[1,0]
	v_pk_mul_f32 v[50:51], v[50:51], v[14:15] op_sel_hi:[1,0]
	v_pk_mul_f32 v[48:49], v[48:49], v[14:15] op_sel_hi:[1,0]
	v_pk_mul_f32 v[46:47], v[46:47], v[14:15] op_sel_hi:[1,0]
	v_pk_mul_f32 v[44:45], v[44:45], v[14:15] op_sel_hi:[1,0]
	v_pk_mul_f32 v[42:43], v[42:43], v[14:15] op_sel_hi:[1,0]
	v_pk_mul_f32 v[40:41], v[40:41], v[14:15] op_sel_hi:[1,0]
	v_pk_mul_f32 v[38:39], v[38:39], v[14:15] op_sel_hi:[1,0]
	v_pk_mul_f32 v[36:37], v[36:37], v[14:15] op_sel_hi:[1,0]
	v_pk_mul_f32 v[34:35], v[34:35], v[14:15] op_sel_hi:[1,0]
	v_pk_mul_f32 v[32:33], v[32:33], v[14:15] op_sel_hi:[1,0]
	v_pk_mul_f32 v[30:31], v[30:31], v[14:15] op_sel_hi:[1,0]
	v_pk_mul_f32 v[28:29], v[28:29], v[14:15] op_sel_hi:[1,0]
	v_pk_mul_f32 v[26:27], v[26:27], v[14:15] op_sel_hi:[1,0]
	v_pk_mul_f32 v[24:25], v[24:25], v[14:15] op_sel_hi:[1,0]
	v_pk_mul_f32 v[22:23], v[22:23], v[14:15] op_sel_hi:[1,0]
	v_pk_mul_f32 v[20:21], v[20:21], v[14:15] op_sel_hi:[1,0]
	v_pk_mul_f32 v[18:19], v[18:19], v[14:15] op_sel_hi:[1,0]
	v_pk_mul_f32 v[16:17], v[16:17], v[14:15] op_sel_hi:[1,0]
.Lmy_pp_nors_a:
	v_sub_f32_e32 v14, v80, v208
	v_exp_f32_e32 v14, v14
	v_mfma_f32_32x32x16_bf16 v[218:233], v[112:115], v[108:111], 0
	v_sub_f32_e32 v80, v81, v208
	v_exp_f32_e32 v80, v80
	v_sub_f32_e32 v81, v82, v208
	v_exp_f32_e32 v81, v81
	v_sub_f32_e32 v82, v83, v208
	v_mfma_f32_32x32x16_bf16 v[218:233], v[10:13], v[104:107], v[218:233]
	v_exp_f32_e32 v82, v82
	v_sub_f32_e32 v83, v84, v208
	v_sub_f32_e32 v84, v85, v208
	v_sub_f32_e32 v85, v86, v208
	v_sub_f32_e32 v86, v87, v208
	v_add_f32_e32 v15, 0, v14
	global_load_lds_dwordx4 v[242:243], off
	global_load_lds_dwordx4 v[242:243], off offset:1024
	v_mfma_f32_32x32x16_bf16 v[218:233], v[6:9], v[100:103], v[218:233]
	v_exp_f32_e32 v83, v83
	v_exp_f32_e32 v84, v84
	v_exp_f32_e32 v85, v85
	v_and_b32_e32 v244, s28, v244
	v_mfma_f32_32x32x16_bf16 v[218:233], v[2:5], v[96:99], v[218:233]
	v_exp_f32_e32 v86, v86
	v_lshl_add_u64 v[242:243], v[244:245], 0, v[242:243]
	s_or_b32 s24, s24, 0x10000
	ds_read_b128 v[112:115], v249
	ds_read_b128 v[10:13], v249 offset:1024
	ds_read_b128 v[6:9], v249 offset:2048
	ds_read_b128 v[2:5], v249 offset:3072
	s_add_i32 s25, s25, 0x4000
	s_and_b32 s25, s25, 0xc000
	v_add_f32_e32 v15, v80, v15
	v_add_f32_e32 v15, v81, v15
	v_add_f32_e32 v15, v82, v15
	v_add_f32_e32 v15, v83, v15
	v_cvt_pk_bf16_f32 v80, v14, v80
	v_cvt_pk_bf16_f32 v81, v81, v82
	v_cvt_pk_bf16_f32 v82, v83, v84
	v_cvt_pk_bf16_f32 v83, v85, v86
	v_sub_f32_e32 v87, v88, v208
	v_sub_f32_e32 v88, v89, v208
	s_waitcnt lgkmcnt(4)
	v_mfma_f32_32x32x16_bf16 v[64:79], v[144:147], v[80:83], v[64:79]
	v_sub_f32_e32 v89, v90, v208
	v_sub_f32_e32 v90, v91, v208
	v_sub_f32_e32 v91, v92, v208
	v_exp_f32_e32 v87, v87
	v_exp_f32_e32 v88, v88
	v_mfma_f32_32x32x16_bf16 v[48:63], v[136:139], v[80:83], v[48:63]
	v_sub_f32_e32 v92, v93, v208
	v_sub_f32_e32 v93, v94, v208
	v_sub_f32_e32 v94, v95, v208
	v_exp_f32_e32 v89, v89
	v_exp_f32_e32 v90, v90
	v_mfma_f32_32x32x16_bf16 v[32:47], v[132:135], v[80:83], v[32:47]
	v_exp_f32_e32 v91, v91
	v_exp_f32_e32 v92, v92
	v_exp_f32_e32 v93, v93
	v_exp_f32_e32 v94, v94
	v_mfma_f32_32x32x16_bf16 v[16:31], v[116:119], v[80:83], v[16:31]
	s_cmp_eq_u32 s29, 0
	s_cbranch_scc1 .Lmy_pp_nbm_a
	s_waitcnt vmcnt(4) lgkmcnt(0)
	s_barrier
.Lmy_pp_nbm_a:
	v_add_f32_e32 v15, v84, v15
	v_add_f32_e32 v15, v85, v15
	v_add_f32_e32 v15, v86, v15
	v_add_f32_e32 v15, v87, v15
	v_cvt_pk_bf16_f32 v84, v87, v88
	v_cvt_pk_bf16_f32 v85, v89, v90
	v_cvt_pk_bf16_f32 v86, v91, v92
	v_cvt_pk_bf16_f32 v87, v93, v94
	v_add_f32_e32 v15, v88, v15
	v_add_f32_e32 v15, v89, v15
	v_mfma_f32_32x32x16_bf16 v[64:79], v[128:131], v[84:87], v[64:79]
	v_add_f32_e32 v15, v90, v15
	v_add_f32_e32 v15, v91, v15
	s_add_i32 s13, s13, -1
	v_mfma_f32_32x32x16_bf16 v[48:63], v[140:143], v[84:87], v[48:63]
	v_add_f32_e32 v15, v92, v15
	v_add_f32_e32 v15, v93, v15
	v_mfma_f32_32x32x16_bf16 v[32:47], v[124:127], v[84:87], v[32:47]
	v_add_f32_e32 v15, v94, v15
	v_add_f32_e32 v0, v0, v15
	v_mfma_f32_32x32x16_bf16 v[16:31], v[120:123], v[84:87], v[16:31]
	s_cmp_lg_u32 s29, 0
	s_cbranch_scc1 .Lmy_pp_nbe_a
	s_waitcnt vmcnt(4) lgkmcnt(0)
	s_barrier
.Lmy_pp_nbe_a:
	v_add_u32_e32 v248, s25, v246
	v_add_u32_e32 v249, s25, v247
	ds_read_b128 v[144:147], v248 offset:8192
	ds_read_b128 v[136:139], v248 offset:10240
	ds_read_b128 v[132:135], v248 offset:12288
	ds_read_b128 v[116:119], v248 offset:14336
	ds_read_b128 v[128:131], v248 offset:9216
	ds_read_b128 v[140:143], v248 offset:11264
	ds_read_b128 v[124:127], v248 offset:13312
	ds_read_b128 v[120:123], v248 offset:15360
	v_max3_f32 v14, v218, v219, v220
	v_max3_f32 v15, v221, v222, v223
	v_max3_f32 v209, v224, v225, v226
	v_max3_f32 v212, v227, v228, v229
	v_max3_f32 v14, v14, v230, v231
	v_max3_f32 v15, v15, v232, v233
	v_max3_f32 v14, v14, v15, v209
	v_max_f32_e32 v14, v14, v212
	v_mov_b32_e32 v15, v14
	s_mov_b32 m0, s24
	s_sub_i32 s28, 5, s29
	s_cmp_gt_u32 s13, s28
	s_cselect_b32 s28, -1, 0
	v_permlane32_swap_b32_e32 v14, v15
	s_add_i32 s24, s24, 0x4000
	s_and_b32 s24, s24, 0xffff
	v_max_f32_e32 v14, v14, v15
	v_add_f32_e32 v15, 0x41000000, v208
	v_cmp_gt_f32_e32 vcc, v14, v15
	s_cbranch_vccz .Lmy_pp_nors_b
	v_max_f32_e32 v15, v208, v14
	v_sub_f32_e32 v14, v208, v15
	v_exp_f32_e32 v14, v14
	v_mov_b32_e32 v208, v15
	s_nop 0
	v_mul_f32_e32 v0, v0, v14
	v_pk_mul_f32 v[78:79], v[78:79], v[14:15] op_sel_hi:[1,0]
	v_pk_mul_f32 v[76:77], v[76:77], v[14:15] op_sel_hi:[1,0]
	v_pk_mul_f32 v[74:75], v[74:75], v[14:15] op_sel_hi:[1,0]
	v_pk_mul_f32 v[72:73], v[72:73], v[14:15] op_sel_hi:[1,0]
	v_pk_mul_f32 v[70:71], v[70:71], v[14:15] op_sel_hi:[1,0]
	v_pk_mul_f32 v[68:69], v[68:69], v[14:15] op_sel_hi:[1,0]
	v_pk_mul_f32 v[66:67], v[66:67], v[14:15] op_sel_hi:[1,0]
	v_pk_mul_f32 v[64:65], v[64:65], v[14:15] op_sel_hi:[1,0]
	v_pk_mul_f32 v[62:63], v[62:63], v[14:15] op_sel_hi:[1,0]
	v_pk_mul_f32 v[60:61], v[60:61], v[14:15] op_sel_hi:[1,0]
	v_pk_mul_f32 v[58:59], v[58:59], v[14:15] op_sel_hi:[1,0]
	v_pk_mul_f32 v[56:57], v[56:57], v[14:15] op_sel_hi:[1,0]
	v_pk_mul_f32 v[54:55], v[54:55], v[14:15] op_sel_hi:[1,0]
	v_pk_mul_f32 v[52:53], v[52:53], v[14:15] op_sel_hi:[1,0]
	v_pk_mul_f32 v[50:51], v[50:51], v[14:15] op_sel_hi:[1,0]
	v_pk_mul_f32 v[48:49], v[48:49], v[14:15] op_sel_hi:[1,0]
	v_pk_mul_f32 v[46:47], v[46:47], v[14:15] op_sel_hi:[1,0]
	v_pk_mul_f32 v[44:45], v[44:45], v[14:15] op_sel_hi:[1,0]
	v_pk_mul_f32 v[42:43], v[42:43], v[14:15] op_sel_hi:[1,0]
	v_pk_mul_f32 v[40:41], v[40:41], v[14:15] op_sel_hi:[1,0]
	v_pk_mul_f32 v[38:39], v[38:39], v[14:15] op_sel_hi:[1,0]
	v_pk_mul_f32 v[36:37], v[36:37], v[14:15] op_sel_hi:[1,0]
	v_pk_mul_f32 v[34:35], v[34:35], v[14:15] op_sel_hi:[1,0]
	v_pk_mul_f32 v[32:33], v[32:33], v[14:15] op_sel_hi:[1,0]
	v_pk_mul_f32 v[30:31], v[30:31], v[14:15] op_sel_hi:[1,0]
	v_pk_mul_f32 v[28:29], v[28:29], v[14:15] op_sel_hi:[1,0]
	v_pk_mul_f32 v[26:27], v[26:27], v[14:15] op_sel_hi:[1,0]
	v_pk_mul_f32 v[24:25], v[24:25], v[14:15] op_sel_hi:[1,0]
	v_pk_mul_f32 v[22:23], v[22:23], v[14:15] op_sel_hi:[1,0]
	v_pk_mul_f32 v[20:21], v[20:21], v[14:15] op_sel_hi:[1,0]
	v_pk_mul_f32 v[18:19], v[18:19], v[14:15] op_sel_hi:[1,0]
	v_pk_mul_f32 v[16:17], v[16:17], v[14:15] op_sel_hi:[1,0]
.Lmy_pp_nors_b:
	v_sub_f32_e32 v14, v218, v208
	v_exp_f32_e32 v14, v14
	v_mfma_f32_32x32x16_bf16 v[80:95], v[112:115], v[108:111], 0
	v_sub_f32_e32 v218, v219, v208
	v_exp_f32_e32 v218, v218
	v_sub_f32_e32 v219, v220, v208
	v_exp_f32_e32 v219, v219
	v_sub_f32_e32 v220, v221, v208
	v_mfma_f32_32x32x16_bf16 v[80:95], v[10:13], v[104:107], v[80:95]
	v_exp_f32_e32 v220, v220
	v_sub_f32_e32 v221, v222, v208
	v_sub_f32_e32 v222, v223, v208
	v_sub_f32_e32 v223, v224, v208
	v_sub_f32_e32 v224, v225, v208
	v_add_f32_e32 v15, 0, v14
	global_load_lds_dwordx4 v[242:243], off
	global_load_lds_dwordx4 v[242:243], off offset:1024
	v_mfma_f32_32x32x16_bf16 v[80:95], v[6:9], v[100:103], v[80:95]
	v_exp_f32_e32 v221, v221
	v_exp_f32_e32 v222, v222
	v_exp_f32_e32 v223, v223
	v_and_b32_e32 v244, s28, v244
	v_mfma_f32_32x32x16_bf16 v[80:95], v[2:5], v[96:99], v[80:95]
	v_exp_f32_e32 v224, v224
	v_lshl_add_u64 v[242:243], v[244:245], 0, v[242:243]
	s_or_b32 s24, s24, 0x10000
	ds_read_b128 v[112:115], v249
	ds_read_b128 v[10:13], v249 offset:1024
	ds_read_b128 v[6:9], v249 offset:2048
	ds_read_b128 v[2:5], v249 offset:3072
	s_add_i32 s25, s25, 0x4000
	s_and_b32 s25, s25, 0xc000
	v_add_f32_e32 v15, v218, v15
	v_add_f32_e32 v15, v219, v15
	v_add_f32_e32 v15, v220, v15
	v_add_f32_e32 v15, v221, v15
	v_cvt_pk_bf16_f32 v218, v14, v218
	v_cvt_pk_bf16_f32 v219, v219, v220
	v_cvt_pk_bf16_f32 v220, v221, v222
	v_cvt_pk_bf16_f32 v221, v223, v224
	v_sub_f32_e32 v225, v226, v208
	v_sub_f32_e32 v226, v227, v208
	s_waitcnt lgkmcnt(4)
	v_mfma_f32_32x32x16_bf16 v[64:79], v[144:147], v[218:221], v[64:79]
	v_sub_f32_e32 v227, v228, v208
	v_sub_f32_e32 v228, v229, v208
	v_sub_f32_e32 v229, v230, v208
	v_exp_f32_e32 v225, v225
	v_exp_f32_e32 v226, v226
	v_mfma_f32_32x32x16_bf16 v[48:63], v[136:139], v[218:221], v[48:63]
	v_sub_f32_e32 v230, v231, v208
	v_sub_f32_e32 v231, v232, v208
	v_sub_f32_e32 v232, v233, v208
	v_exp_f32_e32 v227, v227
	v_exp_f32_e32 v228, v228
	v_mfma_f32_32x32x16_bf16 v[32:47], v[132:135], v[218:221], v[32:47]
	v_exp_f32_e32 v229, v229
	v_exp_f32_e32 v230, v230
	v_exp_f32_e32 v231, v231
	v_exp_f32_e32 v232, v232
	v_mfma_f32_32x32x16_bf16 v[16:31], v[116:119], v[218:221], v[16:31]
	s_cmp_eq_u32 s29, 0
	s_cbranch_scc1 .Lmy_pp_nbm_b
	s_waitcnt vmcnt(4) lgkmcnt(0)
	s_barrier
.Lmy_pp_nbm_b:
	v_add_f32_e32 v15, v222, v15
	v_add_f32_e32 v15, v223, v15
	v_add_f32_e32 v15, v224, v15
	v_add_f32_e32 v15, v225, v15
	v_cvt_pk_bf16_f32 v222, v225, v226
	v_cvt_pk_bf16_f32 v223, v227, v228
	v_cvt_pk_bf16_f32 v224, v229, v230
	v_cvt_pk_bf16_f32 v225, v231, v232
	v_add_f32_e32 v15, v226, v15
	v_add_f32_e32 v15, v227, v15
	v_mfma_f32_32x32x16_bf16 v[64:79], v[128:131], v[222:225], v[64:79]
	v_add_f32_e32 v15, v228, v15
	v_add_f32_e32 v15, v229, v15
	s_add_i32 s13, s13, -1
	v_mfma_f32_32x32x16_bf16 v[48:63], v[140:143], v[222:225], v[48:63]
	v_add_f32_e32 v15, v230, v15
	v_add_f32_e32 v15, v231, v15
	v_mfma_f32_32x32x16_bf16 v[32:47], v[124:127], v[222:225], v[32:47]
	v_add_f32_e32 v15, v232, v15
	v_add_f32_e32 v0, v0, v15
	v_mfma_f32_32x32x16_bf16 v[16:31], v[120:123], v[222:225], v[16:31]
	s_cmp_lg_u32 s29, 0
	s_cbranch_scc1 .Lmy_pp_nbe_b
	s_waitcnt vmcnt(4) lgkmcnt(0)
	s_barrier
.Lmy_pp_nbe_b:
	s_cmp_gt_u32 s13, 1
	s_cbranch_scc1 .Lmy_pp_loop2
	v_add_u32_e32 v248, s25, v246
	v_add_u32_e32 v249, s25, v247
	ds_read_b128 v[144:147], v248 offset:8192
	ds_read_b128 v[136:139], v248 offset:10240
	ds_read_b128 v[132:135], v248 offset:12288
	ds_read_b128 v[116:119], v248 offset:14336
	ds_read_b128 v[128:131], v248 offset:9216
	ds_read_b128 v[140:143], v248 offset:11264
	ds_read_b128 v[124:127], v248 offset:13312
	ds_read_b128 v[120:123], v248 offset:15360
	v_max3_f32 v14, v80, v81, v82
	v_max3_f32 v15, v83, v84, v85
	v_max3_f32 v209, v86, v87, v88
	v_max3_f32 v212, v89, v90, v91
	v_max3_f32 v14, v14, v92, v93
	v_max3_f32 v15, v15, v94, v95
	v_max3_f32 v14, v14, v15, v209
	v_max_f32_e32 v14, v14, v212
	v_mov_b32_e32 v15, v14
	s_mov_b32 m0, s24
	s_sub_i32 s28, 5, s29
	s_cmp_gt_u32 s13, s28
	s_cselect_b32 s28, -1, 0
	v_permlane32_swap_b32_e32 v14, v15
	s_add_i32 s24, s24, 0x4000
	s_and_b32 s24, s24, 0xffff
	v_max_f32_e32 v14, v14, v15
	v_add_f32_e32 v15, 0x41000000, v208
	v_cmp_gt_f32_e32 vcc, v14, v15
	s_cbranch_vccz .Lmy_pp_nors_t
	v_max_f32_e32 v15, v208, v14
	v_sub_f32_e32 v14, v208, v15
	v_exp_f32_e32 v14, v14
	v_mov_b32_e32 v208, v15
	s_nop 0
	v_mul_f32_e32 v0, v0, v14
	v_pk_mul_f32 v[78:79], v[78:79], v[14:15] op_sel_hi:[1,0]
	v_pk_mul_f32 v[76:77], v[76:77], v[14:15] op_sel_hi:[1,0]
	v_pk_mul_f32 v[74:75], v[74:75], v[14:15] op_sel_hi:[1,0]
	v_pk_mul_f32 v[72:73], v[72:73], v[14:15] op_sel_hi:[1,0]
	v_pk_mul_f32 v[70:71], v[70:71], v[14:15] op_sel_hi:[1,0]
	v_pk_mul_f32 v[68:69], v[68:69], v[14:15] op_sel_hi:[1,0]
	v_pk_mul_f32 v[66:67], v[66:67], v[14:15] op_sel_hi:[1,0]
	v_pk_mul_f32 v[64:65], v[64:65], v[14:15] op_sel_hi:[1,0]
	v_pk_mul_f32 v[62:63], v[62:63], v[14:15] op_sel_hi:[1,0]
	v_pk_mul_f32 v[60:61], v[60:61], v[14:15] op_sel_hi:[1,0]
	v_pk_mul_f32 v[58:59], v[58:59], v[14:15] op_sel_hi:[1,0]
	v_pk_mul_f32 v[56:57], v[56:57], v[14:15] op_sel_hi:[1,0]
	v_pk_mul_f32 v[54:55], v[54:55], v[14:15] op_sel_hi:[1,0]
	v_pk_mul_f32 v[52:53], v[52:53], v[14:15] op_sel_hi:[1,0]
	v_pk_mul_f32 v[50:51], v[50:51], v[14:15] op_sel_hi:[1,0]
	v_pk_mul_f32 v[48:49], v[48:49], v[14:15] op_sel_hi:[1,0]
	v_pk_mul_f32 v[46:47], v[46:47], v[14:15] op_sel_hi:[1,0]
	v_pk_mul_f32 v[44:45], v[44:45], v[14:15] op_sel_hi:[1,0]
	v_pk_mul_f32 v[42:43], v[42:43], v[14:15] op_sel_hi:[1,0]
	v_pk_mul_f32 v[40:41], v[40:41], v[14:15] op_sel_hi:[1,0]
	v_pk_mul_f32 v[38:39], v[38:39], v[14:15] op_sel_hi:[1,0]
	v_pk_mul_f32 v[36:37], v[36:37], v[14:15] op_sel_hi:[1,0]
	v_pk_mul_f32 v[34:35], v[34:35], v[14:15] op_sel_hi:[1,0]
	v_pk_mul_f32 v[32:33], v[32:33], v[14:15] op_sel_hi:[1,0]
	v_pk_mul_f32 v[30:31], v[30:31], v[14:15] op_sel_hi:[1,0]
	v_pk_mul_f32 v[28:29], v[28:29], v[14:15] op_sel_hi:[1,0]
	v_pk_mul_f32 v[26:27], v[26:27], v[14:15] op_sel_hi:[1,0]
	v_pk_mul_f32 v[24:25], v[24:25], v[14:15] op_sel_hi:[1,0]
	v_pk_mul_f32 v[22:23], v[22:23], v[14:15] op_sel_hi:[1,0]
	v_pk_mul_f32 v[20:21], v[20:21], v[14:15] op_sel_hi:[1,0]
	v_pk_mul_f32 v[18:19], v[18:19], v[14:15] op_sel_hi:[1,0]
	v_pk_mul_f32 v[16:17], v[16:17], v[14:15] op_sel_hi:[1,0]
.Lmy_pp_nors_t:
	v_sub_f32_e32 v14, v80, v208
	v_exp_f32_e32 v14, v14
	v_mfma_f32_32x32x16_bf16 v[218:233], v[112:115], v[108:111], 0
	v_sub_f32_e32 v80, v81, v208
	v_exp_f32_e32 v80, v80
	v_sub_f32_e32 v81, v82, v208
	v_exp_f32_e32 v81, v81
	v_sub_f32_e32 v82, v83, v208
	v_mfma_f32_32x32x16_bf16 v[218:233], v[10:13], v[104:107], v[218:233]
	v_exp_f32_e32 v82, v82
	v_sub_f32_e32 v83, v84, v208
	v_sub_f32_e32 v84, v85, v208
	v_sub_f32_e32 v85, v86, v208
	v_sub_f32_e32 v86, v87, v208
	v_add_f32_e32 v15, 0, v14
	global_load_lds_dwordx4 v[242:243], off
	global_load_lds_dwordx4 v[242:243], off offset:1024
	v_mfma_f32_32x32x16_bf16 v[218:233], v[6:9], v[100:103], v[218:233]
	v_exp_f32_e32 v83, v83
	v_exp_f32_e32 v84, v84
	v_exp_f32_e32 v85, v85
	v_and_b32_e32 v244, s28, v244
	v_mfma_f32_32x32x16_bf16 v[218:233], v[2:5], v[96:99], v[218:233]
	v_exp_f32_e32 v86, v86
	v_lshl_add_u64 v[242:243], v[244:245], 0, v[242:243]
	s_or_b32 s24, s24, 0x10000
	s_add_i32 s25, s25, 0x4000
	s_and_b32 s25, s25, 0xc000
	v_add_f32_e32 v15, v80, v15
	v_add_f32_e32 v15, v81, v15
	v_add_f32_e32 v15, v82, v15
	v_add_f32_e32 v15, v83, v15
	v_cvt_pk_bf16_f32 v80, v14, v80
	v_cvt_pk_bf16_f32 v81, v81, v82
	v_cvt_pk_bf16_f32 v82, v83, v84
	v_cvt_pk_bf16_f32 v83, v85, v86
	v_sub_f32_e32 v87, v88, v208
	v_sub_f32_e32 v88, v89, v208
	s_waitcnt lgkmcnt(0)
	v_mfma_f32_32x32x16_bf16 v[64:79], v[144:147], v[80:83], v[64:79]
	v_sub_f32_e32 v89, v90, v208
	v_sub_f32_e32 v90, v91, v208
	v_sub_f32_e32 v91, v92, v208
	v_exp_f32_e32 v87, v87
	v_exp_f32_e32 v88, v88
	v_mfma_f32_32x32x16_bf16 v[48:63], v[136:139], v[80:83], v[48:63]
	v_sub_f32_e32 v92, v93, v208
	v_sub_f32_e32 v93, v94, v208
	v_sub_f32_e32 v94, v95, v208
	v_exp_f32_e32 v89, v89
	v_exp_f32_e32 v90, v90
	v_mfma_f32_32x32x16_bf16 v[32:47], v[132:135], v[80:83], v[32:47]
	v_exp_f32_e32 v91, v91
	v_exp_f32_e32 v92, v92
	v_exp_f32_e32 v93, v93
	v_exp_f32_e32 v94, v94
	v_mfma_f32_32x32x16_bf16 v[16:31], v[116:119], v[80:83], v[16:31]
	s_cmp_eq_u32 s29, 0
	s_cbranch_scc1 .Lmy_pp_nbm_t
	s_waitcnt vmcnt(4) lgkmcnt(0)
	s_barrier
